# dead relu/convert work removed from the ffn1 half-tile epilogues with unreachable padding so every later code address is unchanged
# speedup vs baseline: 1.0047x; 1.0047x over previous
.Lh0_B_163:
	v_lshl_add_u32 v148, s39, 8, v150
	v_max_f32_e32 v124, v124, v124
	v_max_f32_e32 v120, v120, v120
	v_max_f32_e32 v125, v125, v125
	v_max_f32_e32 v121, v121, v121
	v_max_f32_e32 v126, v126, v126
	v_max_f32_e32 v127, v127, v127
	v_lshl_or_b32 v134, s38, 8, v152
	v_ashrrev_i32_e32 v149, 31, v148
	v_max_f32_e32 v124, 0, v124
	v_max_f32_e32 v120, 0, v120
	v_max_f32_e32 v125, 0, v125
	v_max_f32_e32 v121, 0, v121
	v_max_f32_e32 v126, 0, v126
	v_max_f32_e32 v122, v122, v122
	v_max_f32_e32 v127, 0, v127
	v_max_f32_e32 v123, v123, v123
	v_lshlrev_b64 v[136:137], 13, v[148:149]
	v_pk_mul_f32 v[124:125], v[124:125], v[124:125]
	v_pk_mul_f32 v[120:121], v[120:121], v[120:121]
	v_max_f32_e32 v122, 0, v122
	v_max_f32_e32 v123, 0, v123
	v_pk_mul_f32 v[126:127], v[126:127], v[126:127]
	v_ashrrev_i32_e32 v135, 31, v134
	v_pk_mul_f32 v[154:155], v[122:123], v[122:123]
	v_cvt_pk_bf16_f32 v122, v124, v125
	v_cvt_pk_bf16_f32 v123, v126, v127
	v_cvt_pk_bf16_f32 v124, v120, v121
	v_lshl_add_u64 v[126:127], s[8:9], 0, v[136:137]
	v_lshlrev_b64 v[120:121], 1, v[134:135]
	v_cvt_pk_bf16_f32 v125, v154, v155
	v_lshl_add_u64 v[126:127], v[126:127], 0, v[120:121]
	global_store_dwordx4 v[126:127], v[122:125], off
	v_max_f32_e32 v104, v104, v104
	v_max_f32_e32 v105, v105, v105
	v_max_f32_e32 v104, 0, v104
	v_max_f32_e32 v105, 0, v105
	v_max_f32_e32 v108, v108, v108
	v_max_f32_e32 v109, v109, v109
	v_or_b32_e32 v112, 16, v148
	v_pk_mul_f32 v[114:115], v[104:105], v[104:105]
	v_max_f32_e32 v105, v106, v106
	v_ashrrev_i32_e32 v113, 31, v112
	v_max_f32_e32 v108, 0, v108
	v_max_f32_e32 v109, 0, v109
	v_max_f32_e32 v104, v110, v110
	v_max_f32_e32 v106, 0, v105
	v_max_f32_e32 v105, v111, v111
	v_max_f32_e32 v107, v107, v107
	v_lshlrev_b64 v[112:113], 13, v[112:113]
	v_pk_mul_f32 v[108:109], v[108:109], v[108:109]
	v_max_f32_e32 v104, 0, v104
	v_max_f32_e32 v105, 0, v105
	v_max_f32_e32 v107, 0, v107
	v_pk_mul_f32 v[110:111], v[104:105], v[104:105]
	v_pk_mul_f32 v[116:117], v[106:107], v[106:107]
	v_cvt_pk_bf16_f32 v104, v108, v109
	v_lshl_add_u64 v[108:109], s[8:9], 0, v[112:113]
	v_cvt_pk_bf16_f32 v105, v110, v111
	v_cvt_pk_bf16_f32 v106, v114, v115
	v_cvt_pk_bf16_f32 v107, v116, v117
	v_lshl_add_u64 v[108:109], v[108:109], 0, v[120:121]
	global_store_dwordx4 v[108:109], v[104:107], off
	v_max_f32_e32 v88, v88, v88
	v_max_f32_e32 v89, v89, v89
	v_max_f32_e32 v88, 0, v88
	v_max_f32_e32 v89, 0, v89
	v_max_f32_e32 v92, v92, v92
	v_max_f32_e32 v93, v93, v93
	v_or_b32_e32 v96, 32, v148
	v_pk_mul_f32 v[98:99], v[88:89], v[88:89]
	v_max_f32_e32 v89, v90, v90
	v_ashrrev_i32_e32 v97, 31, v96
	v_max_f32_e32 v92, 0, v92
	v_max_f32_e32 v93, 0, v93
	v_max_f32_e32 v88, v94, v94
	v_max_f32_e32 v90, 0, v89
	v_max_f32_e32 v89, v95, v95
	v_max_f32_e32 v91, v91, v91
	v_lshlrev_b64 v[96:97], 13, v[96:97]
	v_pk_mul_f32 v[92:93], v[92:93], v[92:93]
	v_max_f32_e32 v88, 0, v88
	v_max_f32_e32 v89, 0, v89
	v_max_f32_e32 v91, 0, v91
	v_pk_mul_f32 v[94:95], v[88:89], v[88:89]
	v_pk_mul_f32 v[100:101], v[90:91], v[90:91]
	v_cvt_pk_bf16_f32 v88, v92, v93
	v_lshl_add_u64 v[92:93], s[8:9], 0, v[96:97]
	v_cvt_pk_bf16_f32 v89, v94, v95
	v_cvt_pk_bf16_f32 v90, v98, v99
	v_cvt_pk_bf16_f32 v91, v100, v101
	v_lshl_add_u64 v[92:93], v[92:93], 0, v[120:121]
	global_store_dwordx4 v[92:93], v[88:91], off
	v_max_f32_e32 v72, v72, v72
	v_max_f32_e32 v73, v73, v73
	v_max_f32_e32 v72, 0, v72
	v_max_f32_e32 v73, 0, v73
	v_max_f32_e32 v76, v76, v76
	v_max_f32_e32 v77, v77, v77
	v_or_b32_e32 v80, 48, v148
	v_pk_mul_f32 v[82:83], v[72:73], v[72:73]
	v_max_f32_e32 v73, v74, v74
	v_ashrrev_i32_e32 v81, 31, v80
	v_max_f32_e32 v76, 0, v76
	v_max_f32_e32 v77, 0, v77
	v_max_f32_e32 v72, v78, v78
	v_max_f32_e32 v74, 0, v73
	v_max_f32_e32 v73, v79, v79
	v_max_f32_e32 v75, v75, v75
	v_lshlrev_b64 v[80:81], 13, v[80:81]
	v_pk_mul_f32 v[76:77], v[76:77], v[76:77]
	v_max_f32_e32 v72, 0, v72
	v_max_f32_e32 v73, 0, v73
	v_max_f32_e32 v75, 0, v75
	v_pk_mul_f32 v[78:79], v[72:73], v[72:73]
	v_pk_mul_f32 v[84:85], v[74:75], v[74:75]
	v_cvt_pk_bf16_f32 v72, v76, v77
	v_lshl_add_u64 v[76:77], s[8:9], 0, v[80:81]
	v_cvt_pk_bf16_f32 v73, v78, v79
	v_cvt_pk_bf16_f32 v74, v82, v83
	v_cvt_pk_bf16_f32 v75, v84, v85
	v_lshl_add_u64 v[76:77], v[76:77], 0, v[120:121]
	global_store_dwordx4 v[76:77], v[72:75], off
	v_max_f32_e32 v56, v56, v56
	v_max_f32_e32 v57, v57, v57
	v_max_f32_e32 v56, 0, v56
	v_max_f32_e32 v57, 0, v57
	v_max_f32_e32 v60, v60, v60
	v_max_f32_e32 v61, v61, v61
	v_add_u32_e32 v64, 0x80, v148
	v_pk_mul_f32 v[66:67], v[56:57], v[56:57]
	v_max_f32_e32 v57, v58, v58
	v_ashrrev_i32_e32 v65, 31, v64
	v_max_f32_e32 v60, 0, v60
	v_max_f32_e32 v61, 0, v61
	v_max_f32_e32 v56, v62, v62
	v_max_f32_e32 v58, 0, v57
	v_max_f32_e32 v57, v63, v63
	v_max_f32_e32 v59, v59, v59
	v_lshlrev_b64 v[64:65], 13, v[64:65]
	v_pk_mul_f32 v[60:61], v[60:61], v[60:61]
	v_max_f32_e32 v56, 0, v56
	v_max_f32_e32 v57, 0, v57
	v_max_f32_e32 v59, 0, v59
	v_pk_mul_f32 v[62:63], v[56:57], v[56:57]
	v_pk_mul_f32 v[68:69], v[58:59], v[58:59]
	v_cvt_pk_bf16_f32 v56, v60, v61
	v_lshl_add_u64 v[60:61], s[8:9], 0, v[64:65]
	v_cvt_pk_bf16_f32 v57, v62, v63
	v_cvt_pk_bf16_f32 v58, v66, v67
	v_cvt_pk_bf16_f32 v59, v68, v69
	v_lshl_add_u64 v[60:61], v[60:61], 0, v[120:121]
	global_store_dwordx4 v[60:61], v[56:59], off
	v_max_f32_e32 v40, v40, v40
	v_max_f32_e32 v41, v41, v41
	v_max_f32_e32 v40, 0, v40
	v_max_f32_e32 v41, 0, v41
	v_max_f32_e32 v44, v44, v44
	v_max_f32_e32 v45, v45, v45
	v_add_u32_e32 v48, 0x90, v148
	v_pk_mul_f32 v[50:51], v[40:41], v[40:41]
	v_max_f32_e32 v41, v42, v42
	v_ashrrev_i32_e32 v49, 31, v48
	v_max_f32_e32 v44, 0, v44
	v_max_f32_e32 v45, 0, v45
	v_max_f32_e32 v40, v46, v46
	v_max_f32_e32 v42, 0, v41
	v_max_f32_e32 v41, v47, v47
	v_max_f32_e32 v43, v43, v43
	v_lshlrev_b64 v[48:49], 13, v[48:49]
	v_pk_mul_f32 v[44:45], v[44:45], v[44:45]
	v_max_f32_e32 v40, 0, v40
	v_max_f32_e32 v41, 0, v41
	v_max_f32_e32 v43, 0, v43
	v_pk_mul_f32 v[46:47], v[40:41], v[40:41]
	v_pk_mul_f32 v[52:53], v[42:43], v[42:43]
	v_cvt_pk_bf16_f32 v40, v44, v45
	v_lshl_add_u64 v[44:45], s[8:9], 0, v[48:49]
	v_cvt_pk_bf16_f32 v41, v46, v47
	v_cvt_pk_bf16_f32 v42, v50, v51
	v_cvt_pk_bf16_f32 v43, v52, v53
	v_lshl_add_u64 v[44:45], v[44:45], 0, v[120:121]
	global_store_dwordx4 v[44:45], v[40:43], off
	v_max_f32_e32 v24, v24, v24
	v_max_f32_e32 v25, v25, v25
	v_max_f32_e32 v24, 0, v24
	v_max_f32_e32 v25, 0, v25
	v_max_f32_e32 v28, v28, v28
	v_max_f32_e32 v29, v29, v29
	v_add_u32_e32 v32, 0xa0, v148
	v_pk_mul_f32 v[34:35], v[24:25], v[24:25]
	v_max_f32_e32 v25, v26, v26
	v_ashrrev_i32_e32 v33, 31, v32
	v_max_f32_e32 v28, 0, v28
	v_max_f32_e32 v29, 0, v29
	v_max_f32_e32 v24, v30, v30
	v_max_f32_e32 v26, 0, v25
	v_max_f32_e32 v25, v31, v31
	v_max_f32_e32 v27, v27, v27
	v_lshlrev_b64 v[32:33], 13, v[32:33]
	v_pk_mul_f32 v[28:29], v[28:29], v[28:29]
	v_max_f32_e32 v24, 0, v24
	v_max_f32_e32 v25, 0, v25
	v_max_f32_e32 v27, 0, v27
	v_pk_mul_f32 v[30:31], v[24:25], v[24:25]
	v_pk_mul_f32 v[36:37], v[26:27], v[26:27]
	v_cvt_pk_bf16_f32 v24, v28, v29
	v_lshl_add_u64 v[28:29], s[8:9], 0, v[32:33]
	v_cvt_pk_bf16_f32 v25, v30, v31
	v_cvt_pk_bf16_f32 v26, v34, v35
	v_cvt_pk_bf16_f32 v27, v36, v37
	v_lshl_add_u64 v[28:29], v[28:29], 0, v[120:121]
	global_store_dwordx4 v[28:29], v[24:27], off
	v_max_f32_e32 v8, v8, v8
	v_max_f32_e32 v9, v9, v9
	v_max_f32_e32 v8, 0, v8
	v_max_f32_e32 v9, 0, v9
	v_max_f32_e32 v12, v12, v12
	v_max_f32_e32 v13, v13, v13
	v_add_u32_e32 v16, 0xb0, v148
	v_pk_mul_f32 v[18:19], v[8:9], v[8:9]
	v_max_f32_e32 v9, v10, v10
	v_ashrrev_i32_e32 v17, 31, v16
	v_max_f32_e32 v12, 0, v12
	v_max_f32_e32 v13, 0, v13
	v_max_f32_e32 v8, v14, v14
	v_max_f32_e32 v10, 0, v9
	v_max_f32_e32 v9, v15, v15
	v_max_f32_e32 v11, v11, v11
	v_lshlrev_b64 v[16:17], 13, v[16:17]
	v_pk_mul_f32 v[12:13], v[12:13], v[12:13]
	v_max_f32_e32 v8, 0, v8
	v_max_f32_e32 v9, 0, v9
	v_max_f32_e32 v11, 0, v11
	v_pk_mul_f32 v[14:15], v[8:9], v[8:9]
	v_pk_mul_f32 v[20:21], v[10:11], v[10:11]
	v_cvt_pk_bf16_f32 v8, v12, v13
	v_lshl_add_u64 v[12:13], s[8:9], 0, v[16:17]
	v_cvt_pk_bf16_f32 v9, v14, v15
	v_cvt_pk_bf16_f32 v10, v18, v19
	v_cvt_pk_bf16_f32 v11, v20, v21
	v_lshl_add_u64 v[12:13], v[12:13], 0, v[120:121]
	global_store_dwordx4 v[12:13], v[8:11], off
	s_andn2_b64 vcc, exec, s[0:1]
	s_mov_b64 s[0:1], -1
	s_movk_i32 s48, 0x90
	s_cbranch_vccnz .LBB0_156
	s_andn2_b64 vcc, exec, s[4:5]
	s_cbranch_vccnz .LBB0_155
	s_barrier
	s_branch .LBB0_155
	s_nop 0
	s_nop 0
	s_nop 0
	s_nop 0
	s_nop 0
	s_nop 0
	s_nop 0
	s_nop 0
	s_nop 0
	s_nop 0
	s_nop 0
	s_nop 0
	s_nop 0
	s_nop 0
	s_nop 0
	s_nop 0
	s_nop 0
	s_nop 0
	s_nop 0
	s_nop 0
	s_nop 0
	s_nop 0
	s_nop 0
	s_nop 0
	s_nop 0
	s_nop 0
	s_nop 0
	s_nop 0
	s_nop 0
	s_nop 0
	s_nop 0
	s_nop 0
	s_nop 0
	s_nop 0
	s_nop 0
	s_nop 0
	s_nop 0
	s_nop 0
	s_nop 0
	s_nop 0
	s_nop 0
	s_nop 0
	s_nop 0
	s_nop 0
	s_nop 0
	s_nop 0
	s_nop 0
	s_nop 0
	s_nop 0
	s_nop 0
	s_nop 0
	s_nop 0
	s_nop 0
	s_nop 0
	s_nop 0
	s_nop 0
	s_nop 0
	s_nop 0
	s_nop 0
	s_nop 0
	s_nop 0
	s_nop 0
	s_nop 0
	s_nop 0
	s_nop 0
	s_nop 0
	s_nop 0
	s_nop 0
	s_nop 0
	s_nop 0
	s_nop 0
	s_nop 0
	s_nop 0
	s_nop 0
	s_nop 0
	s_nop 0
	s_nop 0
	s_nop 0
	s_nop 0
	s_nop 0
	s_nop 0
	s_nop 0
	s_nop 0
	s_nop 0
	s_nop 0
	s_nop 0
	s_nop 0
	s_nop 0
	s_nop 0
	s_nop 0
	s_nop 0
	s_nop 0
	s_nop 0
	s_nop 0
	s_nop 0
	s_nop 0
	s_nop 0
	s_nop 0
	s_nop 0
	s_nop 0
	s_nop 0
	s_nop 0
	s_nop 0
	s_nop 0
	s_nop 0
	s_nop 0
	s_nop 0
	s_nop 0
	s_nop 0
	s_nop 0
	s_nop 0
	s_nop 0
	s_nop 0
	s_nop 0
	s_nop 0
	s_nop 0
	s_nop 0
	s_nop 0
	s_nop 0
	s_nop 0
	s_nop 0
	s_nop 0
	s_nop 0
	s_nop 0
	s_nop 0
	s_nop 0
	s_nop 0
	s_nop 0
	s_nop 0
	s_nop 0
	s_nop 0
	s_nop 0
	s_nop 0
	s_nop 0
	s_nop 0
	s_nop 0
	s_nop 0
	s_nop 0
	s_nop 0
	s_nop 0
	s_nop 0
	s_nop 0
	s_nop 0
	s_nop 0
	s_nop 0
	s_nop 0
	s_nop 0
	s_nop 0
	s_nop 0
	s_nop 0
	s_nop 0
	s_nop 0
	s_nop 0
	s_nop 0
	s_nop 0
	s_nop 0
	s_nop 0
	s_nop 0
	s_nop 0
	s_nop 0
	s_nop 0
	s_nop 0
	s_nop 0
	s_nop 0
	s_nop 0
	s_nop 0
	s_nop 0
	s_nop 0
	s_nop 0
	s_nop 0
	s_nop 0
	s_nop 0
	s_nop 0
	s_nop 0
	s_nop 0
	s_nop 0
	s_nop 0
	s_nop 0
	s_nop 0
	s_nop 0
	s_nop 0
	s_nop 0
	s_nop 0
	s_nop 0
	s_nop 0
	s_nop 0
	s_nop 0
	s_nop 0
	s_nop 0
	s_nop 0
	s_nop 0
	s_nop 0
	s_nop 0
	s_nop 0
	s_nop 0
	s_nop 0
	s_nop 0
	s_nop 0
	s_nop 0
	s_nop 0
	s_nop 0
	s_nop 0
	s_nop 0
	s_nop 0
	s_nop 0
	s_nop 0
	s_nop 0
	s_nop 0
	s_nop 0
	s_nop 0
	s_nop 0
	s_nop 0
	s_nop 0
	s_nop 0
	s_nop 0
	s_nop 0
	s_nop 0
	s_nop 0
	s_nop 0
	s_nop 0
	s_nop 0
	s_nop 0
	s_nop 0
	s_nop 0
	s_nop 0
	s_nop 0
	s_nop 0
	s_nop 0
	s_nop 0
	s_nop 0
	s_nop 0
	s_nop 0
	s_nop 0
	s_nop 0
	s_nop 0
	s_nop 0
	s_nop 0
	s_nop 0
	s_nop 0
	s_nop 0
	s_nop 0
	s_nop 0
	s_nop 0
	s_nop 0
	s_nop 0
	s_nop 0
	s_nop 0
	s_nop 0
	s_nop 0
	s_nop 0
	s_nop 0
	s_nop 0
	s_nop 0
	s_nop 0
	s_nop 0
	s_nop 0

.Lh1_B_163:
	v_lshl_add_u32 v148, s39, 8, v150
	v_lshl_or_b32 v134, s38, 8, v152
	v_ashrrev_i32_e32 v149, 31, v148
	v_lshlrev_b64 v[136:137], 13, v[148:149]
	v_ashrrev_i32_e32 v135, 31, v134
	v_lshl_add_u64 v[126:127], s[8:9], 0, v[136:137]
	v_lshlrev_b64 v[120:121], 1, v[134:135]
	v_max_f32_e32 v112, v112, v112
	v_max_f32_e32 v113, v113, v113
	v_lshl_add_u64 v[126:127], v[126:127], 0, v[120:121]
	v_max_f32_e32 v112, 0, v112
	v_max_f32_e32 v113, 0, v113
	v_max_f32_e32 v116, v116, v116
	v_max_f32_e32 v117, v117, v117
	v_pk_mul_f32 v[122:123], v[112:113], v[112:113]
	v_max_f32_e32 v113, v114, v114
	v_max_f32_e32 v112, v118, v118
	v_max_f32_e32 v114, 0, v113
	v_max_f32_e32 v113, v119, v119
	v_max_f32_e32 v115, v115, v115
	v_max_f32_e32 v116, 0, v116
	v_max_f32_e32 v117, 0, v117
	v_max_f32_e32 v112, 0, v112
	v_max_f32_e32 v113, 0, v113
	v_max_f32_e32 v115, 0, v115
	v_pk_mul_f32 v[116:117], v[116:117], v[116:117]
	v_pk_mul_f32 v[118:119], v[112:113], v[112:113]
	v_pk_mul_f32 v[124:125], v[114:115], v[114:115]
	v_cvt_pk_bf16_f32 v112, v116, v117
	v_cvt_pk_bf16_f32 v113, v118, v119
	v_cvt_pk_bf16_f32 v114, v122, v123
	v_cvt_pk_bf16_f32 v115, v124, v125
	global_store_dwordx4 v[126:127], v[112:115], off offset:256
	s_nop 1
	v_or_b32_e32 v112, 16, v148
	v_ashrrev_i32_e32 v113, 31, v112
	v_lshlrev_b64 v[112:113], 13, v[112:113]
	v_lshl_add_u64 v[108:109], s[8:9], 0, v[112:113]
	v_max_f32_e32 v96, v96, v96
	v_max_f32_e32 v97, v97, v97
	v_lshl_add_u64 v[108:109], v[108:109], 0, v[120:121]
	v_max_f32_e32 v96, 0, v96
	v_max_f32_e32 v97, 0, v97
	v_max_f32_e32 v100, v100, v100
	v_max_f32_e32 v101, v101, v101
	v_pk_mul_f32 v[104:105], v[96:97], v[96:97]
	v_max_f32_e32 v97, v98, v98
	v_max_f32_e32 v96, v102, v102
	v_max_f32_e32 v98, 0, v97
	v_max_f32_e32 v97, v103, v103
	v_max_f32_e32 v99, v99, v99
	v_max_f32_e32 v100, 0, v100
	v_max_f32_e32 v101, 0, v101
	v_max_f32_e32 v96, 0, v96
	v_max_f32_e32 v97, 0, v97
	v_max_f32_e32 v99, 0, v99
	v_pk_mul_f32 v[100:101], v[100:101], v[100:101]
	v_pk_mul_f32 v[102:103], v[96:97], v[96:97]
	v_pk_mul_f32 v[106:107], v[98:99], v[98:99]
	v_cvt_pk_bf16_f32 v96, v100, v101
	v_cvt_pk_bf16_f32 v97, v102, v103
	v_cvt_pk_bf16_f32 v98, v104, v105
	v_cvt_pk_bf16_f32 v99, v106, v107
	global_store_dwordx4 v[108:109], v[96:99], off offset:256
	s_nop 1
	v_or_b32_e32 v96, 32, v148
	v_ashrrev_i32_e32 v97, 31, v96
	v_lshlrev_b64 v[96:97], 13, v[96:97]
	v_lshl_add_u64 v[92:93], s[8:9], 0, v[96:97]
	v_max_f32_e32 v80, v80, v80
	v_max_f32_e32 v81, v81, v81
	v_lshl_add_u64 v[92:93], v[92:93], 0, v[120:121]
	v_max_f32_e32 v80, 0, v80
	v_max_f32_e32 v81, 0, v81
	v_max_f32_e32 v84, v84, v84
	v_max_f32_e32 v85, v85, v85
	v_pk_mul_f32 v[88:89], v[80:81], v[80:81]
	v_max_f32_e32 v81, v82, v82
	v_max_f32_e32 v80, v86, v86
	v_max_f32_e32 v82, 0, v81
	v_max_f32_e32 v81, v87, v87
	v_max_f32_e32 v83, v83, v83
	v_max_f32_e32 v84, 0, v84
	v_max_f32_e32 v85, 0, v85
	v_max_f32_e32 v80, 0, v80
	v_max_f32_e32 v81, 0, v81
	v_max_f32_e32 v83, 0, v83
	v_pk_mul_f32 v[84:85], v[84:85], v[84:85]
	v_pk_mul_f32 v[86:87], v[80:81], v[80:81]
	v_pk_mul_f32 v[90:91], v[82:83], v[82:83]
	v_cvt_pk_bf16_f32 v80, v84, v85
	v_cvt_pk_bf16_f32 v81, v86, v87
	v_cvt_pk_bf16_f32 v82, v88, v89
	v_cvt_pk_bf16_f32 v83, v90, v91
	global_store_dwordx4 v[92:93], v[80:83], off offset:256
	s_nop 1
	v_or_b32_e32 v80, 48, v148
	v_ashrrev_i32_e32 v81, 31, v80
	v_lshlrev_b64 v[80:81], 13, v[80:81]
	v_lshl_add_u64 v[76:77], s[8:9], 0, v[80:81]
	v_max_f32_e32 v64, v64, v64
	v_max_f32_e32 v65, v65, v65
	v_lshl_add_u64 v[76:77], v[76:77], 0, v[120:121]
	v_max_f32_e32 v64, 0, v64
	v_max_f32_e32 v65, 0, v65
	v_max_f32_e32 v68, v68, v68
	v_max_f32_e32 v69, v69, v69
	v_pk_mul_f32 v[72:73], v[64:65], v[64:65]
	v_max_f32_e32 v65, v66, v66
	v_max_f32_e32 v64, v70, v70
	v_max_f32_e32 v66, 0, v65
	v_max_f32_e32 v65, v71, v71
	v_max_f32_e32 v67, v67, v67
	v_max_f32_e32 v68, 0, v68
	v_max_f32_e32 v69, 0, v69
	v_max_f32_e32 v64, 0, v64
	v_max_f32_e32 v65, 0, v65
	v_max_f32_e32 v67, 0, v67
	v_pk_mul_f32 v[68:69], v[68:69], v[68:69]
	v_pk_mul_f32 v[70:71], v[64:65], v[64:65]
	v_pk_mul_f32 v[74:75], v[66:67], v[66:67]
	v_cvt_pk_bf16_f32 v64, v68, v69
	v_cvt_pk_bf16_f32 v65, v70, v71
	v_cvt_pk_bf16_f32 v66, v72, v73
	v_cvt_pk_bf16_f32 v67, v74, v75
	global_store_dwordx4 v[76:77], v[64:67], off offset:256
	s_nop 1
	v_add_u32_e32 v64, 0x80, v148
	v_ashrrev_i32_e32 v65, 31, v64
	v_lshlrev_b64 v[64:65], 13, v[64:65]
	v_lshl_add_u64 v[60:61], s[8:9], 0, v[64:65]
	v_max_f32_e32 v48, v48, v48
	v_max_f32_e32 v49, v49, v49
	v_lshl_add_u64 v[60:61], v[60:61], 0, v[120:121]
	v_max_f32_e32 v48, 0, v48
	v_max_f32_e32 v49, 0, v49
	v_max_f32_e32 v52, v52, v52
	v_max_f32_e32 v53, v53, v53
	v_pk_mul_f32 v[56:57], v[48:49], v[48:49]
	v_max_f32_e32 v49, v50, v50
	v_max_f32_e32 v48, v54, v54
	v_max_f32_e32 v50, 0, v49
	v_max_f32_e32 v49, v55, v55
	v_max_f32_e32 v51, v51, v51
	v_max_f32_e32 v52, 0, v52
	v_max_f32_e32 v53, 0, v53
	v_max_f32_e32 v48, 0, v48
	v_max_f32_e32 v49, 0, v49
	v_max_f32_e32 v51, 0, v51
	v_pk_mul_f32 v[52:53], v[52:53], v[52:53]
	v_pk_mul_f32 v[54:55], v[48:49], v[48:49]
	v_pk_mul_f32 v[58:59], v[50:51], v[50:51]
	v_cvt_pk_bf16_f32 v48, v52, v53
	v_cvt_pk_bf16_f32 v49, v54, v55
	v_cvt_pk_bf16_f32 v50, v56, v57
	v_cvt_pk_bf16_f32 v51, v58, v59
	global_store_dwordx4 v[60:61], v[48:51], off offset:256
	s_nop 1
	v_add_u32_e32 v48, 0x90, v148
	v_ashrrev_i32_e32 v49, 31, v48
	v_lshlrev_b64 v[48:49], 13, v[48:49]
	v_lshl_add_u64 v[44:45], s[8:9], 0, v[48:49]
	v_max_f32_e32 v32, v32, v32
	v_max_f32_e32 v33, v33, v33
	v_lshl_add_u64 v[44:45], v[44:45], 0, v[120:121]
	v_max_f32_e32 v32, 0, v32
	v_max_f32_e32 v33, 0, v33
	v_max_f32_e32 v36, v36, v36
	v_max_f32_e32 v37, v37, v37
	v_pk_mul_f32 v[40:41], v[32:33], v[32:33]
	v_max_f32_e32 v33, v34, v34
	v_max_f32_e32 v32, v38, v38
	v_max_f32_e32 v34, 0, v33
	v_max_f32_e32 v33, v39, v39
	v_max_f32_e32 v35, v35, v35
	v_max_f32_e32 v36, 0, v36
	v_max_f32_e32 v37, 0, v37
	v_max_f32_e32 v32, 0, v32
	v_max_f32_e32 v33, 0, v33
	v_max_f32_e32 v35, 0, v35
	v_pk_mul_f32 v[36:37], v[36:37], v[36:37]
	v_pk_mul_f32 v[38:39], v[32:33], v[32:33]
	v_pk_mul_f32 v[42:43], v[34:35], v[34:35]
	v_cvt_pk_bf16_f32 v32, v36, v37
	v_cvt_pk_bf16_f32 v33, v38, v39
	v_cvt_pk_bf16_f32 v34, v40, v41
	v_cvt_pk_bf16_f32 v35, v42, v43
	global_store_dwordx4 v[44:45], v[32:35], off offset:256
	s_nop 1
	v_add_u32_e32 v32, 0xa0, v148
	v_ashrrev_i32_e32 v33, 31, v32
	v_lshlrev_b64 v[32:33], 13, v[32:33]
	v_lshl_add_u64 v[28:29], s[8:9], 0, v[32:33]
	v_max_f32_e32 v16, v16, v16
	v_max_f32_e32 v17, v17, v17
	v_lshl_add_u64 v[28:29], v[28:29], 0, v[120:121]
	v_max_f32_e32 v16, 0, v16
	v_max_f32_e32 v17, 0, v17
	v_max_f32_e32 v20, v20, v20
	v_max_f32_e32 v21, v21, v21
	v_pk_mul_f32 v[24:25], v[16:17], v[16:17]
	v_max_f32_e32 v17, v18, v18
	v_max_f32_e32 v16, v22, v22
	v_max_f32_e32 v18, 0, v17
	v_max_f32_e32 v17, v23, v23
	v_max_f32_e32 v19, v19, v19
	v_max_f32_e32 v20, 0, v20
	v_max_f32_e32 v21, 0, v21
	v_max_f32_e32 v16, 0, v16
	v_max_f32_e32 v17, 0, v17
	v_max_f32_e32 v19, 0, v19
	v_pk_mul_f32 v[20:21], v[20:21], v[20:21]
	v_pk_mul_f32 v[22:23], v[16:17], v[16:17]
	v_pk_mul_f32 v[26:27], v[18:19], v[18:19]
	v_cvt_pk_bf16_f32 v16, v20, v21
	v_cvt_pk_bf16_f32 v17, v22, v23
	v_cvt_pk_bf16_f32 v18, v24, v25
	v_cvt_pk_bf16_f32 v19, v26, v27
	global_store_dwordx4 v[28:29], v[16:19], off offset:256
	s_nop 1
	v_add_u32_e32 v16, 0xb0, v148
	v_ashrrev_i32_e32 v17, 31, v16
	v_lshlrev_b64 v[16:17], 13, v[16:17]
	v_lshl_add_u64 v[12:13], s[8:9], 0, v[16:17]
	v_max_f32_e32 v0, v0, v0
	v_max_f32_e32 v1, v1, v1
	v_lshl_add_u64 v[12:13], v[12:13], 0, v[120:121]
	v_max_f32_e32 v0, 0, v0
	v_max_f32_e32 v1, 0, v1
	v_max_f32_e32 v4, v4, v4
	v_max_f32_e32 v5, v5, v5
	v_pk_mul_f32 v[8:9], v[0:1], v[0:1]
	v_max_f32_e32 v1, v2, v2
	v_max_f32_e32 v0, v6, v6
	v_max_f32_e32 v2, 0, v1
	v_max_f32_e32 v1, v7, v7
	v_max_f32_e32 v3, v3, v3
	v_max_f32_e32 v4, 0, v4
	v_max_f32_e32 v5, 0, v5
	v_max_f32_e32 v0, 0, v0
	v_max_f32_e32 v1, 0, v1
	v_max_f32_e32 v3, 0, v3
	v_pk_mul_f32 v[4:5], v[4:5], v[4:5]
	v_pk_mul_f32 v[6:7], v[0:1], v[0:1]
	v_pk_mul_f32 v[10:11], v[2:3], v[2:3]
	v_cvt_pk_bf16_f32 v0, v4, v5
	v_cvt_pk_bf16_f32 v1, v6, v7
	v_cvt_pk_bf16_f32 v2, v8, v9
	v_cvt_pk_bf16_f32 v3, v10, v11
	s_andn2_b64 vcc, exec, s[0:1]
	s_mov_b64 s[0:1], -1
	s_movk_i32 s48, 0x90
	global_store_dwordx4 v[12:13], v[0:3], off offset:256
	s_cbranch_vccnz .LBB0_156
	s_andn2_b64 vcc, exec, s[4:5]
	s_cbranch_vccnz .LBB0_155
	s_barrier
	s_branch .LBB0_155
	s_nop 0
	s_nop 0
	s_nop 0
	s_nop 0
	s_nop 0
	s_nop 0
	s_nop 0
	s_nop 0
	s_nop 0
	s_nop 0
	s_nop 0
	s_nop 0
	s_nop 0
	s_nop 0
	s_nop 0
	s_nop 0
	s_nop 0
	s_nop 0
	s_nop 0
	s_nop 0
	s_nop 0
	s_nop 0
	s_nop 0
	s_nop 0
	s_nop 0
	s_nop 0
	s_nop 0
	s_nop 0
	s_nop 0
	s_nop 0
	s_nop 0
	s_nop 0
	s_nop 0
	s_nop 0
	s_nop 0
	s_nop 0
	s_nop 0
	s_nop 0
	s_nop 0
	s_nop 0
	s_nop 0
	s_nop 0
	s_nop 0
	s_nop 0
	s_nop 0
	s_nop 0
	s_nop 0
	s_nop 0
	s_nop 0
	s_nop 0
	s_nop 0
	s_nop 0
	s_nop 0
	s_nop 0
	s_nop 0
	s_nop 0
	s_nop 0
	s_nop 0
	s_nop 0
	s_nop 0
	s_nop 0
	s_nop 0
	s_nop 0
	s_nop 0
	s_nop 0
	s_nop 0
	s_nop 0
	s_nop 0
	s_nop 0
	s_nop 0
	s_nop 0
	s_nop 0
	s_nop 0
	s_nop 0
	s_nop 0
	s_nop 0
	s_nop 0
	s_nop 0
	s_nop 0
	s_nop 0
	s_nop 0
	s_nop 0
	s_nop 0
	s_nop 0
	s_nop 0
	s_nop 0
	s_nop 0
	s_nop 0
	s_nop 0
	s_nop 0
	s_nop 0
	s_nop 0
	s_nop 0
	s_nop 0
	s_nop 0
	s_nop 0
	s_nop 0
	s_nop 0
	s_nop 0
	s_nop 0
	s_nop 0
	s_nop 0
	s_nop 0
	s_nop 0
	s_nop 0
	s_nop 0
	s_nop 0
	s_nop 0
	s_nop 0
	s_nop 0
	s_nop 0
	s_nop 0
	s_nop 0
	s_nop 0
	s_nop 0
	s_nop 0
	s_nop 0
	s_nop 0
	s_nop 0
	s_nop 0
	s_nop 0
	s_nop 0
	s_nop 0
	s_nop 0
	s_nop 0
	s_nop 0
	s_nop 0
	s_nop 0
	s_nop 0
	s_nop 0
	s_nop 0
	s_nop 0
	s_nop 0
	s_nop 0
	s_nop 0
	s_nop 0
	s_nop 0
	s_nop 0
	s_nop 0
	s_nop 0
	s_nop 0
	s_nop 0
	s_nop 0
	s_nop 0
	s_nop 0
	s_nop 0
	s_nop 0
	s_nop 0
	s_nop 0
	s_nop 0
	s_nop 0
	s_nop 0
	s_nop 0
	s_nop 0
	s_nop 0
	s_nop 0
	s_nop 0
	s_nop 0
	s_nop 0
	s_nop 0
	s_nop 0
	s_nop 0
	s_nop 0
	s_nop 0
	s_nop 0
	s_nop 0
	s_nop 0
	s_nop 0
	s_nop 0
	s_nop 0
	s_nop 0
	s_nop 0
	s_nop 0
	s_nop 0
	s_nop 0
	s_nop 0
	s_nop 0
	s_nop 0
	s_nop 0
	s_nop 0
	s_nop 0
	s_nop 0
	s_nop 0
	s_nop 0
	s_nop 0
	s_nop 0
	s_nop 0
	s_nop 0
	s_nop 0
	s_nop 0
	s_nop 0
	s_nop 0
	s_nop 0
	s_nop 0
	s_nop 0
	s_nop 0
	s_nop 0
	s_nop 0
	s_nop 0
	s_nop 0
	s_nop 0
	s_nop 0
	s_nop 0
	s_nop 0
	s_nop 0
	s_nop 0
	s_nop 0
	s_nop 0
	s_nop 0
	s_nop 0
	s_nop 0
	s_nop 0
	s_nop 0
	s_nop 0
	s_nop 0
	s_nop 0
	s_nop 0
	s_nop 0
	s_nop 0
	s_nop 0
	s_nop 0
	s_nop 0
	s_nop 0
	s_nop 0
	s_nop 0
	s_nop 0
	s_nop 0
	s_nop 0
	s_nop 0
	s_nop 0
	s_nop 0
	s_nop 0
	s_nop 0
	s_nop 0
	s_nop 0
	s_nop 0
	s_nop 0
	s_nop 0
	s_nop 0
	s_nop 0
	s_nop 0
	s_nop 0
	s_nop 0
	s_nop 0
	s_nop 0
	s_nop 0
	s_nop 0
	s_nop 0
	s_nop 0
